# sample attention tile body rewritten by hand: 4 key groups unrolled, one online-softmax step per 64-key tile (single correction in P.V), next-tile LDS-DMA issued inside key group 0
# speedup vs baseline: 1.0142x; 1.0142x over previous
.LBB0_803:
	v_lshrrev_b32_e32 v45, 4, v43
	v_lshlrev_b32_e32 v34, 2, v43
	v_and_b32_e32 v34, 12, v34
	v_bfe_u32 v35, v43, 2, 2
	v_add_u32_e32 v38, 8, v45
	v_add_u32_e32 v37, 4, v45
	v_bitop3_b32 v47, v34, v38, v35 bitop3:0x36
	v_add_u32_e32 v38, 12, v45
	s_cmp_eq_u32 s10, 64
	v_bitop3_b32 v36, v34, v45, v35 bitop3:0x36
	v_bitop3_b32 v37, v34, v37, v35 bitop3:0x36
	v_bitop3_b32 v46, v34, v38, v35 bitop3:0x36
	v_lshl_add_u64 v[34:35], v[192:193], 0, s[24:25]
	s_cselect_b64 s[22:23], -1, 0
	v_lshlrev_b64 v[34:35], 7, v[34:35]
	s_add_u32 s10, s15, s24
	v_lshl_add_u64 v[38:39], v[196:197], 0, v[34:35]
	s_addc_u32 s11, s17, s25
	v_lshlrev_b32_e32 v34, 8, v43
	s_lshl_b64 s[10:11], s[10:11], 10
	v_and_b32_e32 v34, 0xf00, v34
	v_lshrrev_b32_e32 v44, 2, v43
	v_lshl_add_u64 v[40:41], v[212:213], 0, s[10:11]
	v_lshl_add_u32 v46, v46, 4, v34
	v_lshl_add_u32 v47, v47, 4, v34
	v_lshl_add_u32 v48, v37, 4, v34
	v_lshl_add_u32 v49, v36, 4, v34
	s_and_b64 vcc, exec, s[20:21]
	s_mov_b64 s[24:25], 0x400
	v_add_u32_e32 v207, 0xb800, v219
	v_add_u32_e32 v208, v219, v216
	ds_read_b128 v[34:37], v49
	ds_read_b128 v[182:185], v48
	ds_read_b128 v[186:189], v47
	ds_read_b128 v[202:205], v46
	s_waitcnt lgkmcnt(2)
	v_mfma_f32_16x16x32_bf16 v[226:229], v[50:53], v[34:37], 0
	v_mfma_f32_16x16x32_bf16 v[230:233], v[82:85], v[34:37], 0
	v_mfma_f32_16x16x32_bf16 v[234:237], v[114:117], v[34:37], 0
	v_mfma_f32_16x16x32_bf16 v[238:241], v[146:149], v[34:37], 0
	s_cbranch_vccz .Lsa_nd0
	s_add_i32 m0, s35, 0xf400
	s_nop 0
	global_load_lds_dwordx4 v[40:41], off nt
	v_lshl_add_u64 v[40:41], v[40:41], 0, s[24:25]
.Lsa_nd0:
	v_mfma_f32_16x16x32_bf16 v[226:229], v[54:57], v[182:185], v[226:229]
	v_mfma_f32_16x16x32_bf16 v[230:233], v[86:89], v[182:185], v[230:233]
	v_mfma_f32_16x16x32_bf16 v[234:237], v[118:121], v[182:185], v[234:237]
	v_mfma_f32_16x16x32_bf16 v[238:241], v[150:153], v[182:185], v[238:241]
	s_cbranch_vccz .Lsa_nd1
	s_add_i32 m0, s35, 0xf800
	s_nop 0
	global_load_lds_dwordx4 v[40:41], off nt
	v_lshl_add_u64 v[40:41], v[40:41], 0, s[24:25]
.Lsa_nd1:
	ds_read_b128 v[34:37], v49 offset:16384
	ds_read_b128 v[182:185], v48 offset:16384
	s_waitcnt lgkmcnt(2)
	v_mfma_f32_16x16x32_bf16 v[226:229], v[58:61], v[186:189], v[226:229]
	v_mfma_f32_16x16x32_bf16 v[230:233], v[90:93], v[186:189], v[230:233]
	v_mfma_f32_16x16x32_bf16 v[234:237], v[122:125], v[186:189], v[234:237]
	v_mfma_f32_16x16x32_bf16 v[238:241], v[154:157], v[186:189], v[238:241]
	s_cbranch_vccz .Lsa_nd2
	s_add_i32 m0, s35, 0xfc00
	s_nop 0
	global_load_lds_dwordx4 v[40:41], off nt
	v_lshl_add_u64 v[40:41], v[40:41], 0, s[24:25]
.Lsa_nd2:
	v_mfma_f32_16x16x32_bf16 v[226:229], v[62:65], v[202:205], v[226:229]
	v_mfma_f32_16x16x32_bf16 v[230:233], v[94:97], v[202:205], v[230:233]
	v_mfma_f32_16x16x32_bf16 v[234:237], v[126:129], v[202:205], v[234:237]
	v_mfma_f32_16x16x32_bf16 v[238:241], v[158:161], v[202:205], v[238:241]
	s_cbranch_vccz .Lsa_nd3
	s_add_i32 m0, s35, 0x10000
	s_nop 0
	global_load_lds_dwordx4 v[40:41], off nt
	v_lshl_add_u64 v[40:41], v[40:41], 0, s[24:25]
.Lsa_nd3:
	ds_read_b128 v[186:189], v47 offset:16384
	ds_read_b128 v[202:205], v46 offset:16384
	s_waitcnt lgkmcnt(2)
	v_mfma_f32_16x16x32_bf16 v[226:229], v[66:69], v[34:37], v[226:229]
	v_mfma_f32_16x16x32_bf16 v[230:233], v[98:101], v[34:37], v[230:233]
	v_mfma_f32_16x16x32_bf16 v[234:237], v[130:133], v[34:37], v[234:237]
	v_mfma_f32_16x16x32_bf16 v[238:241], v[162:165], v[34:37], v[238:241]
	s_cbranch_vccz .Lsa_nd4
	s_add_i32 m0, s35, 0x10400
	s_nop 0
	global_load_lds_dwordx4 v[40:41], off nt
	v_lshl_add_u64 v[40:41], v[40:41], 0, s[24:25]
.Lsa_nd4:
	v_mfma_f32_16x16x32_bf16 v[226:229], v[70:73], v[182:185], v[226:229]
	v_mfma_f32_16x16x32_bf16 v[230:233], v[102:105], v[182:185], v[230:233]
	v_mfma_f32_16x16x32_bf16 v[234:237], v[134:137], v[182:185], v[234:237]
	v_mfma_f32_16x16x32_bf16 v[238:241], v[166:169], v[182:185], v[238:241]
	s_cbranch_vccz .Lsa_nd5
	s_add_i32 m0, s35, 0x10800
	s_nop 0
	global_load_lds_dwordx4 v[40:41], off nt
	v_lshl_add_u64 v[40:41], v[40:41], 0, s[24:25]
.Lsa_nd5:
	ds_read2_b64 v[34:37], v207 offset1:4
	ds_read2_b64 v[182:185], v207 offset0:8 offset1:12
	s_waitcnt lgkmcnt(2)
	v_mfma_f32_16x16x32_bf16 v[226:229], v[74:77], v[186:189], v[226:229]
	v_mfma_f32_16x16x32_bf16 v[230:233], v[106:109], v[186:189], v[230:233]
	v_mfma_f32_16x16x32_bf16 v[234:237], v[138:141], v[186:189], v[234:237]
	v_mfma_f32_16x16x32_bf16 v[238:241], v[170:173], v[186:189], v[238:241]
	s_cbranch_vccz .Lsa_nd6
	s_add_i32 m0, s35, 0x10c00
	s_nop 0
	global_load_lds_dwordx4 v[40:41], off nt
	v_lshl_add_u64 v[40:41], v[40:41], 0, s[24:25]
.Lsa_nd6:
	v_mfma_f32_16x16x32_bf16 v[226:229], v[78:81], v[202:205], v[226:229]
	v_mfma_f32_16x16x32_bf16 v[230:233], v[110:113], v[202:205], v[230:233]
	v_mfma_f32_16x16x32_bf16 v[234:237], v[142:145], v[202:205], v[234:237]
	v_mfma_f32_16x16x32_bf16 v[238:241], v[174:177], v[202:205], v[238:241]
	ds_read_b128 v[186:189], v225 offset:0
	ds_read_b128 v[202:205], v208 offset:47232
	s_cbranch_vccz .Lsa_nd7
	s_add_i32 m0, s35, 0x11000
	s_nop 0
	global_load_lds_dwordx4 v[40:41], off nt
.Lsa_nd7:
	s_cbranch_vccz .Lsa_nd8
	s_mov_b32 m0, s36
	s_nop 0
	global_load_lds_dwordx4 v[38:39], off nt
.Lsa_nd8:
	s_nop 5
	v_mul_f32_e32 v206, v227, v227
	v_mul_f32_e32 v209, v231, v231
	v_fmac_f32_e32 v206, v226, v226
	v_fmac_f32_e32 v209, v230, v230
	v_fmac_f32_e32 v206, v228, v228
	v_fmac_f32_e32 v209, v232, v232
	v_fmac_f32_e32 v206, v229, v229
	v_fmac_f32_e32 v209, v233, v233
	v_add_f32_e32 v206, v206, v209
	v_mul_f32_e32 v209, v235, v235
	v_fmac_f32_e32 v209, v234, v234
	v_fmac_f32_e32 v209, v236, v236
	v_fmac_f32_e32 v209, v237, v237
	v_add_f32_e32 v206, v206, v209
	v_mul_f32_e32 v209, v239, v239
	v_fmac_f32_e32 v209, v238, v238
	v_fmac_f32_e32 v209, v240, v240
	v_fmac_f32_e32 v209, v241, v241
	v_add_f32_e32 v206, v206, v209
	v_mov_b32_e32 v209, v206
	s_nop 1
	v_permlane16_swap_b32_e32 v206, v209
	v_add_f32_e32 v206, v206, v209
	v_mov_b32_e32 v209, v206
	s_nop 1
	v_permlane32_swap_b32_e32 v206, v209
	v_add_f32_e32 v206, v206, v209
	v_mov_b32_e32 v209, 0x358637bd
	v_fmamk_f32 v206, v206, 0x3c800000, v209
	v_rsq_f32_e32 v206, v206
	s_nop 0
	v_pk_mul_f32 v[226:227], v[226:227], v[206:207] op_sel_hi:[1,0]
	v_pk_mul_f32 v[228:229], v[228:229], v[206:207] op_sel_hi:[1,0]
	v_pk_mul_f32 v[230:231], v[230:231], v[206:207] op_sel_hi:[1,0]
	v_pk_mul_f32 v[232:233], v[232:233], v[206:207] op_sel_hi:[1,0]
	v_pk_mul_f32 v[234:235], v[234:235], v[206:207] op_sel_hi:[1,0]
	v_pk_mul_f32 v[236:237], v[236:237], v[206:207] op_sel_hi:[1,0]
	v_pk_mul_f32 v[238:239], v[238:239], v[206:207] op_sel_hi:[1,0]
	v_pk_mul_f32 v[240:241], v[240:241], v[206:207] op_sel_hi:[1,0]
	v_cvt_pk_bf16_f32 v226, v226, v227
	v_cvt_pk_bf16_f32 v227, v228, v229
	v_cvt_pk_bf16_f32 v228, v230, v231
	v_cvt_pk_bf16_f32 v229, v232, v233
	v_cvt_pk_bf16_f32 v234, v234, v235
	v_cvt_pk_bf16_f32 v235, v236, v237
	v_cvt_pk_bf16_f32 v236, v238, v239
	v_cvt_pk_bf16_f32 v237, v240, v241
	ds_read_b128 v[230:233], v49 offset:4096
	ds_read_b128 v[238:241], v48 offset:4096
	s_waitcnt lgkmcnt(2)
	v_mfma_f32_16x16x32_bf16 v[38:41], v[226:229], v[34:37], 0
	v_mfma_f32_16x16x32_bf16 v[38:41], v[234:237], v[182:185], v[38:41]
	v_mfma_f32_16x16x32_bf16 v[38:41], v[186:189], v[202:205], v[38:41]
	ds_read_b128 v[34:37], v47 offset:4096
	ds_read_b128 v[182:185], v46 offset:4096
	s_waitcnt lgkmcnt(2)
	v_mfma_f32_16x16x32_bf16 v[226:229], v[50:53], v[230:233], 0
	v_mfma_f32_16x16x32_bf16 v[234:237], v[82:85], v[230:233], 0
	v_mfma_f32_16x16x32_bf16 v[186:189], v[114:117], v[230:233], 0
	v_mfma_f32_16x16x32_bf16 v[202:205], v[146:149], v[230:233], 0
	v_mfma_f32_16x16x32_bf16 v[226:229], v[54:57], v[238:241], v[226:229]
	v_mfma_f32_16x16x32_bf16 v[234:237], v[86:89], v[238:241], v[234:237]
	v_mfma_f32_16x16x32_bf16 v[186:189], v[118:121], v[238:241], v[186:189]
	v_mfma_f32_16x16x32_bf16 v[202:205], v[150:153], v[238:241], v[202:205]
	ds_read_b128 v[230:233], v49 offset:20480
	ds_read_b128 v[238:241], v48 offset:20480
	s_waitcnt lgkmcnt(2)
	v_mfma_f32_16x16x32_bf16 v[226:229], v[58:61], v[34:37], v[226:229]
	v_mfma_f32_16x16x32_bf16 v[234:237], v[90:93], v[34:37], v[234:237]
	v_mfma_f32_16x16x32_bf16 v[186:189], v[122:125], v[34:37], v[186:189]
	v_mfma_f32_16x16x32_bf16 v[202:205], v[154:157], v[34:37], v[202:205]
	v_mfma_f32_16x16x32_bf16 v[226:229], v[62:65], v[182:185], v[226:229]
	v_mfma_f32_16x16x32_bf16 v[234:237], v[94:97], v[182:185], v[234:237]
	v_mfma_f32_16x16x32_bf16 v[186:189], v[126:129], v[182:185], v[186:189]
	v_mfma_f32_16x16x32_bf16 v[202:205], v[158:161], v[182:185], v[202:205]
	ds_read_b128 v[34:37], v47 offset:20480
	ds_read_b128 v[182:185], v46 offset:20480
	s_waitcnt lgkmcnt(2)
	v_mfma_f32_16x16x32_bf16 v[226:229], v[66:69], v[230:233], v[226:229]
	v_mfma_f32_16x16x32_bf16 v[234:237], v[98:101], v[230:233], v[234:237]
	v_mfma_f32_16x16x32_bf16 v[186:189], v[130:133], v[230:233], v[186:189]
	v_mfma_f32_16x16x32_bf16 v[202:205], v[162:165], v[230:233], v[202:205]
	v_mfma_f32_16x16x32_bf16 v[226:229], v[70:73], v[238:241], v[226:229]
	v_mfma_f32_16x16x32_bf16 v[234:237], v[102:105], v[238:241], v[234:237]
	v_mfma_f32_16x16x32_bf16 v[186:189], v[134:137], v[238:241], v[186:189]
	v_mfma_f32_16x16x32_bf16 v[202:205], v[166:169], v[238:241], v[202:205]
	ds_read2_b64 v[230:233], v207 offset1:4
	ds_read2_b64 v[238:241], v207 offset0:8 offset1:12
	s_waitcnt lgkmcnt(2)
	v_mfma_f32_16x16x32_bf16 v[226:229], v[74:77], v[34:37], v[226:229]
	v_mfma_f32_16x16x32_bf16 v[234:237], v[106:109], v[34:37], v[234:237]
	v_mfma_f32_16x16x32_bf16 v[186:189], v[138:141], v[34:37], v[186:189]
	v_mfma_f32_16x16x32_bf16 v[202:205], v[170:173], v[34:37], v[202:205]
	v_mfma_f32_16x16x32_bf16 v[226:229], v[78:81], v[182:185], v[226:229]
	v_mfma_f32_16x16x32_bf16 v[234:237], v[110:113], v[182:185], v[234:237]
	v_mfma_f32_16x16x32_bf16 v[186:189], v[142:145], v[182:185], v[186:189]
	v_mfma_f32_16x16x32_bf16 v[202:205], v[174:177], v[182:185], v[202:205]
	ds_read_b128 v[34:37], v225 offset:1280
	ds_read_b128 v[182:185], v208 offset:47232
	s_nop 5
	v_mul_f32_e32 v206, v227, v227
	v_mul_f32_e32 v209, v235, v235
	v_fmac_f32_e32 v206, v226, v226
	v_fmac_f32_e32 v209, v234, v234
	v_fmac_f32_e32 v206, v228, v228
	v_fmac_f32_e32 v209, v236, v236
	v_fmac_f32_e32 v206, v229, v229
	v_fmac_f32_e32 v209, v237, v237
	v_add_f32_e32 v206, v206, v209
	v_mul_f32_e32 v209, v187, v187
	v_fmac_f32_e32 v209, v186, v186
	v_fmac_f32_e32 v209, v188, v188
	v_fmac_f32_e32 v209, v189, v189
	v_add_f32_e32 v206, v206, v209
	v_mul_f32_e32 v209, v203, v203
	v_fmac_f32_e32 v209, v202, v202
	v_fmac_f32_e32 v209, v204, v204
	v_fmac_f32_e32 v209, v205, v205
	v_add_f32_e32 v206, v206, v209
	v_mov_b32_e32 v209, v206
	s_nop 1
	v_permlane16_swap_b32_e32 v206, v209
	v_add_f32_e32 v206, v206, v209
	v_mov_b32_e32 v209, v206
	s_nop 1
	v_permlane32_swap_b32_e32 v206, v209
	v_add_f32_e32 v206, v206, v209
	v_mov_b32_e32 v209, 0x358637bd
	v_fmamk_f32 v206, v206, 0x3c800000, v209
	v_rsq_f32_e32 v206, v206
	s_nop 0
	v_pk_mul_f32 v[226:227], v[226:227], v[206:207] op_sel_hi:[1,0]
	v_pk_mul_f32 v[228:229], v[228:229], v[206:207] op_sel_hi:[1,0]
	v_pk_mul_f32 v[234:235], v[234:235], v[206:207] op_sel_hi:[1,0]
	v_pk_mul_f32 v[236:237], v[236:237], v[206:207] op_sel_hi:[1,0]
	v_pk_mul_f32 v[186:187], v[186:187], v[206:207] op_sel_hi:[1,0]
	v_pk_mul_f32 v[188:189], v[188:189], v[206:207] op_sel_hi:[1,0]
	v_pk_mul_f32 v[202:203], v[202:203], v[206:207] op_sel_hi:[1,0]
	v_pk_mul_f32 v[204:205], v[204:205], v[206:207] op_sel_hi:[1,0]
	v_cvt_pk_bf16_f32 v226, v226, v227
	v_cvt_pk_bf16_f32 v227, v228, v229
	v_cvt_pk_bf16_f32 v228, v234, v235
	v_cvt_pk_bf16_f32 v229, v236, v237
	v_cvt_pk_bf16_f32 v186, v186, v187
	v_cvt_pk_bf16_f32 v187, v188, v189
	v_cvt_pk_bf16_f32 v188, v202, v203
	v_cvt_pk_bf16_f32 v189, v204, v205
	ds_read_b128 v[234:237], v49 offset:8192
	ds_read_b128 v[202:205], v48 offset:8192
	s_waitcnt lgkmcnt(2)
	v_mfma_f32_16x16x32_bf16 v[178:181], v[226:229], v[230:233], 0
	v_mfma_f32_16x16x32_bf16 v[178:181], v[186:189], v[238:241], v[178:181]
	v_mfma_f32_16x16x32_bf16 v[178:181], v[34:37], v[182:185], v[178:181]
	ds_read_b128 v[230:233], v47 offset:8192
	ds_read_b128 v[238:241], v46 offset:8192
	s_waitcnt lgkmcnt(2)
	v_mfma_f32_16x16x32_bf16 v[226:229], v[50:53], v[234:237], 0
	v_mfma_f32_16x16x32_bf16 v[186:189], v[82:85], v[234:237], 0
	v_mfma_f32_16x16x32_bf16 v[34:37], v[114:117], v[234:237], 0
	v_mfma_f32_16x16x32_bf16 v[182:185], v[146:149], v[234:237], 0
	v_mfma_f32_16x16x32_bf16 v[226:229], v[54:57], v[202:205], v[226:229]
	v_mfma_f32_16x16x32_bf16 v[186:189], v[86:89], v[202:205], v[186:189]
	v_mfma_f32_16x16x32_bf16 v[34:37], v[118:121], v[202:205], v[34:37]
	v_mfma_f32_16x16x32_bf16 v[182:185], v[150:153], v[202:205], v[182:185]
	ds_read_b128 v[234:237], v49 offset:24576
	ds_read_b128 v[202:205], v48 offset:24576
	s_waitcnt lgkmcnt(2)
	v_mfma_f32_16x16x32_bf16 v[226:229], v[58:61], v[230:233], v[226:229]
	v_mfma_f32_16x16x32_bf16 v[186:189], v[90:93], v[230:233], v[186:189]
	v_mfma_f32_16x16x32_bf16 v[34:37], v[122:125], v[230:233], v[34:37]
	v_mfma_f32_16x16x32_bf16 v[182:185], v[154:157], v[230:233], v[182:185]
	v_mfma_f32_16x16x32_bf16 v[226:229], v[62:65], v[238:241], v[226:229]
	v_mfma_f32_16x16x32_bf16 v[186:189], v[94:97], v[238:241], v[186:189]
	v_mfma_f32_16x16x32_bf16 v[34:37], v[126:129], v[238:241], v[34:37]
	v_mfma_f32_16x16x32_bf16 v[182:185], v[158:161], v[238:241], v[182:185]
	ds_read_b128 v[230:233], v47 offset:24576
	ds_read_b128 v[238:241], v46 offset:24576
	s_waitcnt lgkmcnt(2)
	v_mfma_f32_16x16x32_bf16 v[226:229], v[66:69], v[234:237], v[226:229]
	v_mfma_f32_16x16x32_bf16 v[186:189], v[98:101], v[234:237], v[186:189]
	v_mfma_f32_16x16x32_bf16 v[34:37], v[130:133], v[234:237], v[34:37]
	v_mfma_f32_16x16x32_bf16 v[182:185], v[162:165], v[234:237], v[182:185]
	v_mfma_f32_16x16x32_bf16 v[226:229], v[70:73], v[202:205], v[226:229]
	v_mfma_f32_16x16x32_bf16 v[186:189], v[102:105], v[202:205], v[186:189]
	v_mfma_f32_16x16x32_bf16 v[34:37], v[134:137], v[202:205], v[34:37]
	v_mfma_f32_16x16x32_bf16 v[182:185], v[166:169], v[202:205], v[182:185]
	ds_read2_b64 v[234:237], v207 offset1:4
	ds_read2_b64 v[202:205], v207 offset0:8 offset1:12
	s_waitcnt lgkmcnt(2)
	v_mfma_f32_16x16x32_bf16 v[226:229], v[74:77], v[230:233], v[226:229]
	v_mfma_f32_16x16x32_bf16 v[186:189], v[106:109], v[230:233], v[186:189]
	v_mfma_f32_16x16x32_bf16 v[34:37], v[138:141], v[230:233], v[34:37]
	v_mfma_f32_16x16x32_bf16 v[182:185], v[170:173], v[230:233], v[182:185]
	v_mfma_f32_16x16x32_bf16 v[226:229], v[78:81], v[238:241], v[226:229]
	v_mfma_f32_16x16x32_bf16 v[186:189], v[110:113], v[238:241], v[186:189]
	v_mfma_f32_16x16x32_bf16 v[34:37], v[142:145], v[238:241], v[34:37]
	v_mfma_f32_16x16x32_bf16 v[182:185], v[174:177], v[238:241], v[182:185]
	ds_read_b128 v[230:233], v225 offset:2560
	ds_read_b128 v[238:241], v208 offset:47232
	s_nop 5
	v_mul_f32_e32 v206, v227, v227
	v_mul_f32_e32 v209, v187, v187
	v_fmac_f32_e32 v206, v226, v226
	v_fmac_f32_e32 v209, v186, v186
	v_fmac_f32_e32 v206, v228, v228
	v_fmac_f32_e32 v209, v188, v188
	v_fmac_f32_e32 v206, v229, v229
	v_fmac_f32_e32 v209, v189, v189
	v_add_f32_e32 v206, v206, v209
	v_mul_f32_e32 v209, v35, v35
	v_fmac_f32_e32 v209, v34, v34
	v_fmac_f32_e32 v209, v36, v36
	v_fmac_f32_e32 v209, v37, v37
	v_add_f32_e32 v206, v206, v209
	v_mul_f32_e32 v209, v183, v183
	v_fmac_f32_e32 v209, v182, v182
	v_fmac_f32_e32 v209, v184, v184
	v_fmac_f32_e32 v209, v185, v185
	v_add_f32_e32 v206, v206, v209
	v_mov_b32_e32 v209, v206
	s_nop 1
	v_permlane16_swap_b32_e32 v206, v209
	v_add_f32_e32 v206, v206, v209
	v_mov_b32_e32 v209, v206
	s_nop 1
	v_permlane32_swap_b32_e32 v206, v209
	v_add_f32_e32 v206, v206, v209
	v_mov_b32_e32 v209, 0x358637bd
	v_fmamk_f32 v206, v206, 0x3c800000, v209
	v_rsq_f32_e32 v206, v206
	s_nop 0
	v_pk_mul_f32 v[226:227], v[226:227], v[206:207] op_sel_hi:[1,0]
	v_pk_mul_f32 v[228:229], v[228:229], v[206:207] op_sel_hi:[1,0]
	v_pk_mul_f32 v[186:187], v[186:187], v[206:207] op_sel_hi:[1,0]
	v_pk_mul_f32 v[188:189], v[188:189], v[206:207] op_sel_hi:[1,0]
	v_pk_mul_f32 v[34:35], v[34:35], v[206:207] op_sel_hi:[1,0]
	v_pk_mul_f32 v[36:37], v[36:37], v[206:207] op_sel_hi:[1,0]
	v_pk_mul_f32 v[182:183], v[182:183], v[206:207] op_sel_hi:[1,0]
	v_pk_mul_f32 v[184:185], v[184:185], v[206:207] op_sel_hi:[1,0]
	v_cvt_pk_bf16_f32 v226, v226, v227
	v_cvt_pk_bf16_f32 v227, v228, v229
	v_cvt_pk_bf16_f32 v228, v186, v187
	v_cvt_pk_bf16_f32 v229, v188, v189
	v_cvt_pk_bf16_f32 v34, v34, v35
	v_cvt_pk_bf16_f32 v35, v36, v37
	v_cvt_pk_bf16_f32 v36, v182, v183
	v_cvt_pk_bf16_f32 v37, v184, v185
	ds_read_b128 v[186:189], v49 offset:12288
	ds_read_b128 v[182:185], v48 offset:12288
	s_waitcnt lgkmcnt(2)
	v_mfma_f32_16x16x32_bf16 v[242:245], v[226:229], v[234:237], 0
	v_mfma_f32_16x16x32_bf16 v[242:245], v[34:37], v[202:205], v[242:245]
	v_mfma_f32_16x16x32_bf16 v[242:245], v[230:233], v[238:241], v[242:245]
	ds_read_b128 v[234:237], v47 offset:12288
	ds_read_b128 v[202:205], v46 offset:12288
	s_waitcnt lgkmcnt(2)
	v_mfma_f32_16x16x32_bf16 v[226:229], v[50:53], v[186:189], 0
	v_mfma_f32_16x16x32_bf16 v[34:37], v[82:85], v[186:189], 0
	v_mfma_f32_16x16x32_bf16 v[230:233], v[114:117], v[186:189], 0
	v_mfma_f32_16x16x32_bf16 v[238:241], v[146:149], v[186:189], 0
	v_mfma_f32_16x16x32_bf16 v[226:229], v[54:57], v[182:185], v[226:229]
	v_mfma_f32_16x16x32_bf16 v[34:37], v[86:89], v[182:185], v[34:37]
	v_mfma_f32_16x16x32_bf16 v[230:233], v[118:121], v[182:185], v[230:233]
	v_mfma_f32_16x16x32_bf16 v[238:241], v[150:153], v[182:185], v[238:241]
	ds_read_b128 v[186:189], v49 offset:28672
	ds_read_b128 v[182:185], v48 offset:28672
	s_waitcnt lgkmcnt(2)
	v_mfma_f32_16x16x32_bf16 v[226:229], v[58:61], v[234:237], v[226:229]
	v_mfma_f32_16x16x32_bf16 v[34:37], v[90:93], v[234:237], v[34:37]
	v_mfma_f32_16x16x32_bf16 v[230:233], v[122:125], v[234:237], v[230:233]
	v_mfma_f32_16x16x32_bf16 v[238:241], v[154:157], v[234:237], v[238:241]
	v_mfma_f32_16x16x32_bf16 v[226:229], v[62:65], v[202:205], v[226:229]
	v_mfma_f32_16x16x32_bf16 v[34:37], v[94:97], v[202:205], v[34:37]
	v_mfma_f32_16x16x32_bf16 v[230:233], v[126:129], v[202:205], v[230:233]
	v_mfma_f32_16x16x32_bf16 v[238:241], v[158:161], v[202:205], v[238:241]
	ds_read_b128 v[234:237], v47 offset:28672
	ds_read_b128 v[202:205], v46 offset:28672
	s_waitcnt lgkmcnt(2)
	v_mfma_f32_16x16x32_bf16 v[226:229], v[66:69], v[186:189], v[226:229]
	v_mfma_f32_16x16x32_bf16 v[34:37], v[98:101], v[186:189], v[34:37]
	v_mfma_f32_16x16x32_bf16 v[230:233], v[130:133], v[186:189], v[230:233]
	v_mfma_f32_16x16x32_bf16 v[238:241], v[162:165], v[186:189], v[238:241]
	v_mfma_f32_16x16x32_bf16 v[226:229], v[70:73], v[182:185], v[226:229]
	v_mfma_f32_16x16x32_bf16 v[34:37], v[102:105], v[182:185], v[34:37]
	v_mfma_f32_16x16x32_bf16 v[230:233], v[134:137], v[182:185], v[230:233]
	v_mfma_f32_16x16x32_bf16 v[238:241], v[166:169], v[182:185], v[238:241]
	ds_read2_b64 v[186:189], v207 offset1:4
	ds_read2_b64 v[182:185], v207 offset0:8 offset1:12
	s_waitcnt lgkmcnt(2)
	v_mfma_f32_16x16x32_bf16 v[226:229], v[74:77], v[234:237], v[226:229]
	v_mfma_f32_16x16x32_bf16 v[34:37], v[106:109], v[234:237], v[34:37]
	v_mfma_f32_16x16x32_bf16 v[230:233], v[138:141], v[234:237], v[230:233]
	v_mfma_f32_16x16x32_bf16 v[238:241], v[170:173], v[234:237], v[238:241]
	v_mfma_f32_16x16x32_bf16 v[226:229], v[78:81], v[202:205], v[226:229]
	v_mfma_f32_16x16x32_bf16 v[34:37], v[110:113], v[202:205], v[34:37]
	v_mfma_f32_16x16x32_bf16 v[230:233], v[142:145], v[202:205], v[230:233]
	v_mfma_f32_16x16x32_bf16 v[238:241], v[174:177], v[202:205], v[238:241]
	ds_read_b128 v[234:237], v225 offset:3840
	ds_read_b128 v[202:205], v208 offset:47232
	s_nop 5
	v_mul_f32_e32 v206, v227, v227
	v_mul_f32_e32 v209, v35, v35
	v_fmac_f32_e32 v206, v226, v226
	v_fmac_f32_e32 v209, v34, v34
	v_fmac_f32_e32 v206, v228, v228
	v_fmac_f32_e32 v209, v36, v36
	v_fmac_f32_e32 v206, v229, v229
	v_fmac_f32_e32 v209, v37, v37
	v_add_f32_e32 v206, v206, v209
	v_mul_f32_e32 v209, v231, v231
	v_fmac_f32_e32 v209, v230, v230
	v_fmac_f32_e32 v209, v232, v232
	v_fmac_f32_e32 v209, v233, v233
	v_add_f32_e32 v206, v206, v209
	v_mul_f32_e32 v209, v239, v239
	v_fmac_f32_e32 v209, v238, v238
	v_fmac_f32_e32 v209, v240, v240
	v_fmac_f32_e32 v209, v241, v241
	v_add_f32_e32 v206, v206, v209
	v_mov_b32_e32 v209, v206
	s_nop 1
	v_permlane16_swap_b32_e32 v206, v209
	v_add_f32_e32 v206, v206, v209
	v_mov_b32_e32 v209, v206
	s_nop 1
	v_permlane32_swap_b32_e32 v206, v209
	v_add_f32_e32 v206, v206, v209
	v_mov_b32_e32 v209, 0x358637bd
	v_fmamk_f32 v206, v206, 0x3c800000, v209
	v_rsq_f32_e32 v206, v206
	s_nop 0
	v_pk_mul_f32 v[226:227], v[226:227], v[206:207] op_sel_hi:[1,0]
	v_pk_mul_f32 v[228:229], v[228:229], v[206:207] op_sel_hi:[1,0]
	v_pk_mul_f32 v[34:35], v[34:35], v[206:207] op_sel_hi:[1,0]
	v_pk_mul_f32 v[36:37], v[36:37], v[206:207] op_sel_hi:[1,0]
	v_pk_mul_f32 v[230:231], v[230:231], v[206:207] op_sel_hi:[1,0]
	v_pk_mul_f32 v[232:233], v[232:233], v[206:207] op_sel_hi:[1,0]
	v_pk_mul_f32 v[238:239], v[238:239], v[206:207] op_sel_hi:[1,0]
	v_pk_mul_f32 v[240:241], v[240:241], v[206:207] op_sel_hi:[1,0]
	v_cvt_pk_bf16_f32 v226, v226, v227
	v_cvt_pk_bf16_f32 v227, v228, v229
	v_cvt_pk_bf16_f32 v228, v34, v35
	v_cvt_pk_bf16_f32 v229, v36, v37
	v_cvt_pk_bf16_f32 v230, v230, v231
	v_cvt_pk_bf16_f32 v231, v232, v233
	v_cvt_pk_bf16_f32 v232, v238, v239
	v_cvt_pk_bf16_f32 v233, v240, v241
	s_waitcnt lgkmcnt(0)
	v_mfma_f32_16x16x32_bf16 v[246:249], v[226:229], v[186:189], 0
	v_mfma_f32_16x16x32_bf16 v[246:249], v[230:233], v[182:185], v[246:249]
	v_mfma_f32_16x16x32_bf16 v[246:249], v[234:237], v[202:205], v[246:249]
	s_nop 7
	s_and_b64 vcc, exec, s[22:23]
	s_cbranch_vccz .Lsa_nomask
	v_cmp_le_u32_e32 vcc, v218, v220
	s_nop 1
	v_cndmask_b32_e32 v38, v211, v38, vcc
	v_add_u32_e32 v206, 1, v218
	v_cmp_le_u32_e32 vcc, v206, v220
	s_nop 1
	v_cndmask_b32_e32 v39, v211, v39, vcc
	v_add_u32_e32 v206, 2, v218
	v_cmp_le_u32_e32 vcc, v206, v220
	s_nop 1
	v_cndmask_b32_e32 v40, v211, v40, vcc
	v_add_u32_e32 v206, 3, v218
	v_cmp_le_u32_e32 vcc, v206, v220
	s_nop 1
	v_cndmask_b32_e32 v41, v211, v41, vcc
	v_mov_b32_e32 v178, v211
	v_mov_b32_e32 v179, v211
	v_mov_b32_e32 v180, v211
	v_mov_b32_e32 v181, v211
	v_mov_b32_e32 v242, v211
	v_mov_b32_e32 v243, v211
	v_mov_b32_e32 v244, v211
	v_mov_b32_e32 v245, v211
	v_mov_b32_e32 v246, v211
	v_mov_b32_e32 v247, v211
	v_mov_b32_e32 v248, v211
	v_mov_b32_e32 v249, v211
.Lsa_nomask:
	v_max3_f32 v206, v38, v39, v40
	v_max3_f32 v209, v41, v178, v179
	v_max3_f32 v206, v206, v180, v181
	v_max3_f32 v209, v209, v242, v243
	v_max3_f32 v206, v206, v244, v245
	v_max3_f32 v209, v209, v246, v247
	v_max3_f32 v206, v206, v248, v249
	v_max_f32_e32 v206, v206, v209
	v_mov_b32_e32 v209, v206
	s_nop 1
	v_permlane16_swap_b32_e32 v206, v209
	v_max_f32_e32 v206, v206, v209
	v_mov_b32_e32 v209, v206
	s_nop 1
	v_permlane32_swap_b32_e32 v206, v209
	v_max_f32_e32 v206, v206, v209
	s_mov_b32 s24, 0xf149f2ca
	v_max3_f32 v204, v42, v206, s24
	v_sub_f32_e32 v209, v42, v204
	v_exp_f32_e32 v209, v209
	v_sub_f32_e32 v38, v38, v204
	v_sub_f32_e32 v39, v39, v204
	v_sub_f32_e32 v40, v40, v204
	v_sub_f32_e32 v41, v41, v204
	v_sub_f32_e32 v178, v178, v204
	v_sub_f32_e32 v179, v179, v204
	v_sub_f32_e32 v180, v180, v204
	v_sub_f32_e32 v181, v181, v204
	v_sub_f32_e32 v242, v242, v204
	v_sub_f32_e32 v243, v243, v204
	v_sub_f32_e32 v244, v244, v204
	v_sub_f32_e32 v245, v245, v204
	v_sub_f32_e32 v246, v246, v204
	v_sub_f32_e32 v247, v247, v204
	v_sub_f32_e32 v248, v248, v204
	v_sub_f32_e32 v249, v249, v204
	v_exp_f32_e32 v38, v38
	v_exp_f32_e32 v39, v39
	v_exp_f32_e32 v40, v40
	v_exp_f32_e32 v41, v41
	v_exp_f32_e32 v178, v178
	v_exp_f32_e32 v179, v179
	v_exp_f32_e32 v180, v180
	v_exp_f32_e32 v181, v181
	v_exp_f32_e32 v242, v242
	v_exp_f32_e32 v243, v243
	v_exp_f32_e32 v244, v244
	v_exp_f32_e32 v245, v245
	v_exp_f32_e32 v246, v246
	v_exp_f32_e32 v247, v247
	v_exp_f32_e32 v248, v248
	v_exp_f32_e32 v249, v249
	s_nop 0
	v_add_f32_e32 v206, v38, v39
	v_add_f32_e32 v207, v40, v41
	v_add_f32_e32 v208, v178, v179
	v_add_f32_e32 v206, v206, v208
	v_add_f32_e32 v208, v180, v181
	v_add_f32_e32 v207, v207, v208
	v_add_f32_e32 v208, v242, v243
	v_add_f32_e32 v206, v206, v208
	v_add_f32_e32 v208, v244, v245
	v_add_f32_e32 v207, v207, v208
	v_add_f32_e32 v208, v246, v247
	v_add_f32_e32 v206, v206, v208
	v_add_f32_e32 v208, v248, v249
	v_add_f32_e32 v207, v207, v208
	v_add_f32_e32 v206, v206, v207
	v_fma_f32 v217, v217, v209, v206
	s_and_saveexec_b64 s[24:25], s[0:1]
	s_cbranch_execz .Lsa_pdone
	v_cvt_pk_bf16_f32 v38, v38, v39
	v_cvt_pk_bf16_f32 v39, v40, v41
	ds_write_b64 v224, v[38:39]
	v_cvt_pk_bf16_f32 v178, v178, v179
	v_cvt_pk_bf16_f32 v179, v180, v181
	ds_write_b64 v224, v[178:179] offset:32
	v_cvt_pk_bf16_f32 v242, v242, v243
	v_cvt_pk_bf16_f32 v243, v244, v245
	ds_write_b64 v224, v[242:243] offset:64
	v_cvt_pk_bf16_f32 v246, v246, v247
	v_cvt_pk_bf16_f32 v247, v248, v249
	ds_write_b64 v224, v[246:247] offset:96
	s_and_b64 exec, exec, s[8:9]
	ds_write_b32 v190, v209
.Lsa_pdone:
	s_or_b64 exec, exec, s[24:25]
	v_lshrrev_b32_e32 v34, 3, v43
	v_and_b32_e32 v38, 12, v43
	v_and_or_b32 v34, v34, 2, s40
	v_bfe_u32 v35, v43, 1, 1
	v_and_or_b32 v39, v45, 2, v38
	v_or_b32_e32 v36, v34, v35
	v_lshlrev_b32_e32 v37, 8, v44
	v_bitop3_b32 v34, v34, v39, v35 bitop3:0x36
	v_lshlrev_b32_e32 v35, 3, v43
	v_and_b32_e32 v37, 0xfffffb00, v37
	v_and_b32_e32 v35, 8, v35
	v_lshl_add_u32 v34, v34, 4, s39
	v_add3_u32 v34, v34, v37, v35
	v_or_b32_e32 v37, 4, v44
	v_lshlrev_b32_e32 v39, 8, v37
	v_bfe_u32 v37, v37, 2, 2
	v_bitop3_b32 v36, v37, v36, v38 bitop3:0x36
	v_lshl_add_u32 v36, v36, 4, s39
	v_add3_u32 v35, v36, v39, v35
	v_add_u32_e32 v36, 0x2000, v34
	v_add_u32_e32 v37, 0x2000, v35
	v_add_u32_e32 v40, 0xec00, v221
	s_waitcnt lgkmcnt(0)
	s_barrier
	ds_read2_b32 v[44:45], v40 offset0:52 offset1:84
	ds_read_b64_tr_b16 v[226:227], v34
	ds_read_b64_tr_b16 v[228:229], v35
	ds_read_b64_tr_b16 v[186:187], v34 offset:4096
	ds_read_b64_tr_b16 v[188:189], v35 offset:4096
	ds_read_b64_tr_b16 v[182:183], v36
	ds_read_b64_tr_b16 v[184:185], v37
	ds_read_b64_tr_b16 v[178:179], v36 offset:4096
	ds_read_b64_tr_b16 v[180:181], v37 offset:4096
	s_waitcnt lgkmcnt(8)
	v_pk_mul_f32 v[2:3], v[44:45], v[2:3] op_sel_hi:[0,1]
	v_pk_mul_f32 v[4:5], v[44:45], v[4:5] op_sel_hi:[0,1]
	v_pk_mul_f32 v[6:7], v[44:45], v[6:7] op_sel_hi:[0,1]
	v_pk_mul_f32 v[8:9], v[44:45], v[8:9] op_sel_hi:[0,1]
	v_pk_mul_f32 v[10:11], v[44:45], v[10:11] op_sel_hi:[0,1]
	v_pk_mul_f32 v[12:13], v[44:45], v[12:13] op_sel_hi:[0,1]
	v_pk_mul_f32 v[14:15], v[44:45], v[14:15] op_sel_hi:[0,1]
	v_pk_mul_f32 v[16:17], v[44:45], v[16:17] op_sel_hi:[0,1]
	v_pk_mul_f32 v[18:19], v[44:45], v[18:19] op_sel:[1,0]
	v_pk_mul_f32 v[20:21], v[44:45], v[20:21] op_sel:[1,0]
	v_pk_mul_f32 v[22:23], v[44:45], v[22:23] op_sel:[1,0]
	v_pk_mul_f32 v[24:25], v[44:45], v[24:25] op_sel:[1,0]
	v_pk_mul_f32 v[26:27], v[44:45], v[26:27] op_sel:[1,0]
	v_pk_mul_f32 v[28:29], v[44:45], v[28:29] op_sel:[1,0]
	v_pk_mul_f32 v[30:31], v[44:45], v[30:31] op_sel:[1,0]
	v_pk_mul_f32 v[32:33], v[44:45], v[32:33] op_sel:[1,0]
	s_waitcnt lgkmcnt(4)
	ds_read_b128 v[230:233], v222 offset:37888
	ds_read_b128 v[234:237], v222 offset:42496
	ds_read_b128 v[238:241], v222 offset:37920
	ds_read_b128 v[242:245], v222 offset:42528
	ds_read_b128 v[246:249], v222 offset:37952
	ds_read_b128 v[206:209], v222 offset:42560
	ds_read_b128 v[46:49], v222 offset:37984
	ds_read_b128 v[38:41], v222 offset:42592
	s_waitcnt lgkmcnt(6)
	v_mfma_f32_32x32x16_bf16 v[2:17], v[226:229], v[230:233], v[2:17]
	v_mfma_f32_32x32x16_bf16 v[18:33], v[226:229], v[234:237], v[18:33]
	s_waitcnt lgkmcnt(4)
	v_mfma_f32_32x32x16_bf16 v[2:17], v[186:189], v[238:241], v[2:17]
	v_mfma_f32_32x32x16_bf16 v[18:33], v[186:189], v[242:245], v[18:33]
	s_waitcnt lgkmcnt(2)
	v_mfma_f32_32x32x16_bf16 v[2:17], v[182:185], v[246:249], v[2:17]
	v_mfma_f32_32x32x16_bf16 v[18:33], v[182:185], v[206:209], v[18:33]
	s_waitcnt lgkmcnt(0)
	v_mfma_f32_32x32x16_bf16 v[2:17], v[178:181], v[46:49], v[2:17]
	v_mfma_f32_32x32x16_bf16 v[18:33], v[178:181], v[38:41], v[18:33]
	s_cmp_lt_u32 s41, s37
	s_cbranch_scc0 .LBB0_828
	s_mov_b64 s[10:11], -1
	s_and_b64 vcc, exec, s[18:19]
	s_cbranch_vccz .LBB0_825
	s_waitcnt lgkmcnt(0)
	s_barrier
	s_and_saveexec_b64 s[18:19], s[12:13]
	s_cbranch_execz .LBB0_824
	s_mov_b64 s[20:21], 0
	v_mov_b32_e32 v40, v250
	s_branch .LBB0_818
